# grid barrier: XCD leader publishes the per-XCD generation before its own L1 invalidate instead of after
# speedup vs baseline: 1.0013x; 1.0013x over previous
; DI unsigned xb_ld(unsigned* p) { return __hip_atomic_load(p, __ATOMIC_RELAXED, __HIP_MEMORY_SCOPE_AGENT); }
; DI unsigned xb_add(unsigned* p, unsigned v) { return __hip_atomic_fetch_add(p, v, __ATOMIC_RELAXED, __HIP_MEMORY_SCOPE_AGENT); }
; #define XB_SPIN(cond, bar) do { unsigned _sp = 0; while (cond) { __builtin_amdgcn_s_sleep(1); \
;     if ((++_sp & 255u) == 0u) { if (xb_ld(&(bar)[XB_TMO])) break; if (_sp > XB_SPIN_CAP) { atomicAdd(&(bar)[XB_TMO], 1u); break; } } } } while (0)
; DI void xcd_barrier(const XcdBarrier& b, int wid_s) {
;     ...
;     const unsigned old = xb_add(&bar[XB_XSUB(b.x)], 1u);
;     const unsigned gen = old / nloc;
;     if (old + 1u == (gen + 1u) * nloc) {
;       __builtin_amdgcn_fence(__ATOMIC_RELEASE, "agent");
;       asm volatile("s_waitcnt vmcnt(0)" ::: "memory");
;       const unsigned og = xb_add(&bar[XB_TOP], 1u);
;       const unsigned tg = og / nx;
;       if (og + 1u == (tg + 1u) * nx) xb_add(&bar[XB_TOPGEN], 1u);
;       else XB_SPIN(xb_ld(&bar[XB_TOPGEN]) == tg, bar);
;       __builtin_amdgcn_fence(__ATOMIC_ACQUIRE, "agent");
;       xb_add(&bar[XB_XGEN(b.x)], 1u);
;       asm volatile("s_waitcnt vmcnt(0)" ::: "memory");
;     } else {
;       XB_SPIN(xb_ld(&bar[XB_XGEN(b.x)]) == gen, bar);
;       __builtin_amdgcn_fence(__ATOMIC_ACQUIRE, "agent");
;       asm volatile("s_waitcnt vmcnt(0)" ::: "memory");
.LBB0_72:
	s_or_b64 exec, exec, s[2:3]
	s_mov_b64 s[2:3], exec
	v_mbcnt_lo_u32_b32 v0, s2, 0
	v_mbcnt_hi_u32_b32 v0, s3, v0
	v_cmp_eq_u32_e32 vcc, 0, v0
	s_waitcnt vmcnt(0)
	s_and_saveexec_b64 s[20:21], vcc
	s_cbranch_execz .LBB0_74
	s_bcnt1_i32_b64 s2, s[2:3]
	v_mov_b32_e32 v0, s2
	v_readlane_b32 s2, v253, 7
	v_readlane_b32 s3, v253, 8
	s_nop 4
	global_atomic_add v209, v0, s[2:3]
.LBB0_74:
	s_or_b64 exec, exec, s[20:21]
	buffer_inv sc1
	s_waitcnt vmcnt(0)
